# speedup vs baseline: 1.0104x; 1.0104x over previous
; DI unsigned pack2(float a, float b) { v2f f = {a, b}; return __builtin_bit_cast(unsigned, __builtin_convertvector(f, v2bf)); }
; DI float bflo(unsigned v) { return __uint_as_float(v << 16); }
; DI float bfhi(unsigned v) { return __uint_as_float(v & 0xffff0000u); }
; DI float xsumh(float v) { const u32x2 r = __builtin_amdgcn_permlane32_swap(__float_as_uint(v), __float_as_uint(v), false, false); return __uint_as_float(r[0]) + __uint_as_float(r[1]); }
; DI void nsa_attn_phase(const Params& p, char* smem) {
;     ...
;       l = xsumh(l);
;       const float sc = g_s / fmaxf(l, 1e-30f);
; #pragma unroll
;       for (int dc = 0; dc < 2; ++dc)
; #pragma unroll
;         for (int i = 0; i < 16; ++i) tot[dc][i] += ot[dc][i] * sc;
;     }
;     {
;       m = 0.f; l = 0.f;
; #pragma unroll
;       for (int dc = 0; dc < 2; ++dc)
; #pragma unroll
;         for (int i = 0; i < 16; ++i) ot[dc][i] = 0.f;
;       const u16* kb_ = p.qkvz + (long)b * SEQ * LD + 2048 + hk * 64;
;       const u16* vb_ = p.qkvz + (long)b * SEQ * LD + 2304 + hk * 64;
;       const int lo = (t0 - 511) > 0 ? ((t0 - 511) >> 6) : 0;
;       flash_pass<64, false, true>(smem, kb_, LD, vb_, LD, lo, (tmax >> 6) + 1, nullptr, qf, tq, 1, 512, slope2, t0, tmax, nullptr, qb_w, ot, m, l);
;       l = xsumh(l);
;       const float sc = g_w / fmaxf(l, 1e-30f);
; #pragma unroll
;       for (int dc = 0; dc < 2; ++dc)
; #pragma unroll
;         for (int i = 0; i < 16; ++i) ot[dc][i] = tot[dc][i] + ot[dc][i] * sc;
;     }
; #pragma unroll
;     for (int dc = 0; dc < 2; ++dc)
; #pragma unroll
;       for (int g4 = 0; g4 < 4; ++g4) {
;         const int d = hq * 64 + 32 * dc + 8 * g4 + 4 * h;
;         const u32x2 zz = *(const u32x2*)(p.qkvz + tok * LD + 2560 + d);
;         u32x2 o;
;         o.x = pack2(ot[dc][4 * g4] * bflo(zz.x), ot[dc][4 * g4 + 1] * bfhi(zz.x));
;         o.y = pack2(ot[dc][4 * g4 + 2] * bflo(zz.y), ot[dc][4 * g4 + 3] * bfhi(zz.y));
;         *(u32x2*)(p.u + tok * 1024 + d) = o;
;       }
.LBB0_801:
	v_div_scale_f32 v0, s[0:1], v231, v231, v229
	v_rcp_f32_e32 v2, v0
	s_waitcnt vmcnt(0)
	v_readlane_b32 s4, v255, 28
	v_readlane_b32 s5, v255, 29
	v_fma_f32 v3, -v0, v2, 1.0
	v_fmac_f32_e32 v2, v3, v2
	v_div_scale_f32 v3, vcc, v229, v231, v229
	v_mul_f32_e32 v4, v3, v2
	v_fma_f32 v5, -v0, v4, v3
	v_fmac_f32_e32 v4, v5, v2
	v_fma_f32 v0, -v0, v4, v3
	v_div_fmas_f32 v0, v0, v2, v4
	v_add_f32_e32 v2, v233, v190
	v_max_f32_e32 v2, 0xda24260, v2
	v_div_scale_f32 v3, s[0:1], v2, v2, v228
	v_rcp_f32_e32 v4, v3
	v_div_fixup_f32 v0, v0, v231, v229
	v_readlane_b32 s6, v255, 30
	v_readlane_b32 s7, v255, 31
	v_fma_f32 v5, -v3, v4, 1.0
	v_fmac_f32_e32 v4, v5, v4
	v_div_scale_f32 v5, vcc, v228, v2, v228
	v_mul_f32_e32 v6, v5, v4
	v_fma_f32 v7, -v3, v6, v5
	v_fmac_f32_e32 v6, v7, v4
	v_fma_f32 v3, -v3, v6, v5
	v_div_fmas_f32 v3, v3, v4, v6
	v_div_fixup_f32 v2, v3, v2, v228
	v_pk_mul_f32 v[4:5], v[64:65], v[2:3] op_sel_hi:[1,0]
	s_nop 0
	v_pk_fma_f32 v[64:65], v[32:33], v[0:1], v[4:5] op_sel_hi:[1,0,1]
	v_pk_mul_f32 v[4:5], v[66:67], v[2:3] op_sel_hi:[1,0]
	s_nop 0
	v_pk_fma_f32 v[18:19], v[34:35], v[0:1], v[4:5] op_sel_hi:[1,0,1]
	v_pk_mul_f32 v[4:5], v[68:69], v[2:3] op_sel_hi:[1,0]
	s_nop 0
	v_pk_fma_f32 v[34:35], v[36:37], v[0:1], v[4:5] op_sel_hi:[1,0,1]
	v_pk_mul_f32 v[4:5], v[70:71], v[2:3] op_sel_hi:[1,0]
	s_nop 0
	v_pk_fma_f32 v[32:33], v[38:39], v[0:1], v[4:5] op_sel_hi:[1,0,1]
	v_pk_mul_f32 v[4:5], v[72:73], v[2:3] op_sel_hi:[1,0]
	s_nop 0
	v_pk_fma_f32 v[30:31], v[40:41], v[0:1], v[4:5] op_sel_hi:[1,0,1]
	v_pk_mul_f32 v[4:5], v[74:75], v[2:3] op_sel_hi:[1,0]
	s_nop 0
	v_pk_fma_f32 v[28:29], v[42:43], v[0:1], v[4:5] op_sel_hi:[1,0,1]
	v_pk_mul_f32 v[4:5], v[76:77], v[2:3] op_sel_hi:[1,0]
	s_nop 0
	v_pk_fma_f32 v[26:27], v[44:45], v[0:1], v[4:5] op_sel_hi:[1,0,1]
	v_pk_mul_f32 v[4:5], v[78:79], v[2:3] op_sel_hi:[1,0]
	s_nop 0
	v_pk_fma_f32 v[24:25], v[46:47], v[0:1], v[4:5] op_sel_hi:[1,0,1]
	v_pk_mul_f32 v[4:5], v[80:81], v[2:3] op_sel_hi:[1,0]
	s_nop 0
	v_pk_fma_f32 v[16:17], v[48:49], v[0:1], v[4:5] op_sel_hi:[1,0,1]
	v_pk_mul_f32 v[4:5], v[82:83], v[2:3] op_sel_hi:[1,0]
	s_nop 0
	v_pk_fma_f32 v[14:15], v[50:51], v[0:1], v[4:5] op_sel_hi:[1,0,1]
	v_pk_mul_f32 v[4:5], v[84:85], v[2:3] op_sel_hi:[1,0]
	s_nop 0
	v_pk_fma_f32 v[12:13], v[52:53], v[0:1], v[4:5] op_sel_hi:[1,0,1]
	v_pk_mul_f32 v[4:5], v[86:87], v[2:3] op_sel_hi:[1,0]
	s_nop 0
	v_pk_fma_f32 v[10:11], v[54:55], v[0:1], v[4:5] op_sel_hi:[1,0,1]
	v_pk_mul_f32 v[4:5], v[88:89], v[2:3] op_sel_hi:[1,0]
	s_nop 0
	v_pk_fma_f32 v[8:9], v[56:57], v[0:1], v[4:5] op_sel_hi:[1,0,1]
	v_pk_mul_f32 v[4:5], v[90:91], v[2:3] op_sel_hi:[1,0]
	s_nop 0
	v_pk_fma_f32 v[6:7], v[58:59], v[0:1], v[4:5] op_sel_hi:[1,0,1]
	v_pk_mul_f32 v[4:5], v[92:93], v[2:3] op_sel_hi:[1,0]
	v_pk_mul_f32 v[2:3], v[94:95], v[2:3] op_sel_hi:[1,0]
	v_pk_fma_f32 v[4:5], v[60:61], v[0:1], v[4:5] op_sel_hi:[1,0,1]
	v_pk_fma_f32 v[2:3], v[62:63], v[0:1], v[2:3] op_sel_hi:[1,0,1]
	v_mov_b32_e32 v0, v191
	s_nop 1
	v_permlane32_swap_b32_e32 v191, v0
	v_add_f32_e32 v0, v191, v0
	v_max_f32_e32 v0, 0xda24260, v0
	v_div_scale_f32 v20, s[0:1], v0, v0, v181
	v_rcp_f32_e32 v21, v20
	s_mov_b64 s[0:1], 0x1400
	v_fma_f32 v22, -v20, v21, 1.0
	v_fmac_f32_e32 v21, v22, v21
	v_div_scale_f32 v22, vcc, v181, v0, v181
	v_mul_f32_e32 v23, v22, v21
	v_fma_f32 v36, -v20, v23, v22
	v_fmac_f32_e32 v23, v36, v21
	v_fma_f32 v20, -v20, v23, v22
	v_div_fmas_f32 v20, v20, v21, v23
	v_div_fixup_f32 v0, v20, v0, v181
	v_lshl_or_b32 v20, v226, 2, v180
	v_ashrrev_i32_e32 v21, 31, v20
	v_lshl_add_u64 v[22:23], v[178:179], 0, s[0:1]
	v_lshlrev_b64 v[38:39], 1, v[20:21]
	v_lshl_add_u64 v[40:41], v[22:23], 0, v[38:39]
	global_load_dwordx2 v[162:163], v[40:41], off offset:16
	global_load_dwordx2 v[164:165], v[40:41], off offset:32
	global_load_dwordx2 v[166:167], v[40:41], off offset:48
	global_load_dwordx2 v[168:169], v[40:41], off offset:64
	global_load_dwordx2 v[170:171], v[40:41], off offset:80
	global_load_dwordx2 v[172:173], v[40:41], off offset:96
	global_load_dwordx2 v[174:175], v[40:41], off offset:112
	global_load_dwordx2 v[40:41], v[40:41], off
	v_pk_fma_f32 v[42:43], v[96:97], v[0:1], v[64:65] op_sel_hi:[1,0,1]
	v_pk_fma_f32 v[18:19], v[98:99], v[0:1], v[18:19] op_sel_hi:[1,0,1]
	v_lshlrev_b64 v[36:37], 11, v[176:177]
	v_pk_fma_f32 v[34:35], v[100:101], v[0:1], v[34:35] op_sel_hi:[1,0,1]
	v_pk_fma_f32 v[32:33], v[102:103], v[0:1], v[32:33] op_sel_hi:[1,0,1]
	v_pk_fma_f32 v[30:31], v[104:105], v[0:1], v[30:31] op_sel_hi:[1,0,1]
	v_pk_fma_f32 v[28:29], v[106:107], v[0:1], v[28:29] op_sel_hi:[1,0,1]
	v_pk_fma_f32 v[26:27], v[108:109], v[0:1], v[26:27] op_sel_hi:[1,0,1]
	v_pk_fma_f32 v[24:25], v[110:111], v[0:1], v[24:25] op_sel_hi:[1,0,1]
	v_pk_fma_f32 v[16:17], v[112:113], v[0:1], v[16:17] op_sel_hi:[1,0,1]
	v_pk_fma_f32 v[14:15], v[114:115], v[0:1], v[14:15] op_sel_hi:[1,0,1]
	v_pk_fma_f32 v[12:13], v[116:117], v[0:1], v[12:13] op_sel_hi:[1,0,1]
	v_pk_fma_f32 v[10:11], v[118:119], v[0:1], v[10:11] op_sel_hi:[1,0,1]
	v_pk_fma_f32 v[8:9], v[120:121], v[0:1], v[8:9] op_sel_hi:[1,0,1]
	v_pk_fma_f32 v[6:7], v[122:123], v[0:1], v[6:7] op_sel_hi:[1,0,1]
	v_pk_fma_f32 v[4:5], v[124:125], v[0:1], v[4:5] op_sel_hi:[1,0,1]
	v_pk_fma_f32 v[2:3], v[126:127], v[0:1], v[2:3] op_sel_hi:[1,0,1]
	s_mov_b64 s[0:1], 0
	s_waitcnt vmcnt(0)
; DI unsigned pack2(float a, float b) { v2f f = {a, b}; return __builtin_bit_cast(unsigned, __builtin_convertvector(f, v2bf)); }
; DI float bflo(unsigned v) { return __uint_as_float(v << 16); }
; DI float bfhi(unsigned v) { return __uint_as_float(v & 0xffff0000u); }
; DI void nsa_attn_phase(const Params& p, char* smem) {
;     ...
; #pragma unroll
;     for (int dc = 0; dc < 2; ++dc)
; #pragma unroll
;       for (int g4 = 0; g4 < 4; ++g4) {
;         const int d = hq * 64 + 32 * dc + 8 * g4 + 4 * h;
;         const u32x2 zz = *(const u32x2*)(p.qkvz + tok * LD + 2560 + d);
;         u32x2 o;
;         o.x = pack2(ot[dc][4 * g4] * bflo(zz.x), ot[dc][4 * g4 + 1] * bfhi(zz.x));
;         o.y = pack2(ot[dc][4 * g4 + 2] * bflo(zz.y), ot[dc][4 * g4 + 3] * bfhi(zz.y));
;         *(u32x2*)(p.u + tok * 1024 + d) = o;
;       }
	v_lshlrev_b32_e32 v44, 16, v40
	v_and_b32_e32 v45, 0xffff0000, v40
	v_pk_mul_f32 v[42:43], v[42:43], v[44:45]
	s_nop 0
	v_cvt_pk_bf16_f32 v40, v42, v43
	v_lshlrev_b32_e32 v42, 16, v41
	v_and_b32_e32 v43, 0xffff0000, v41
	v_pk_mul_f32 v[18:19], v[18:19], v[42:43]
	s_nop 0
	v_cvt_pk_bf16_f32 v41, v18, v19
	v_lshl_add_u64 v[18:19], s[4:5], 0, v[36:37]
	v_lshl_add_u64 v[18:19], v[18:19], 0, v[38:39]
	global_store_dwordx2 v[18:19], v[40:41], off
	v_mov_b32_e32 v36, v162
	v_mov_b32_e32 v37, v163
	v_lshlrev_b32_e32 v38, 16, v36
	v_and_b32_e32 v39, 0xffff0000, v36
	v_lshlrev_b32_e32 v36, 16, v37
	v_and_b32_e32 v37, 0xffff0000, v37
	v_pk_mul_f32 v[34:35], v[34:35], v[38:39]
	v_pk_mul_f32 v[32:33], v[32:33], v[36:37]
	v_cvt_pk_bf16_f32 v34, v34, v35
	v_cvt_pk_bf16_f32 v35, v32, v33
	global_store_dwordx2 v[18:19], v[34:35], off offset:16
	v_mov_b32_e32 v32, v164
	v_mov_b32_e32 v33, v165
	v_lshlrev_b32_e32 v34, 16, v32
	v_and_b32_e32 v35, 0xffff0000, v32
	v_lshlrev_b32_e32 v32, 16, v33
	v_and_b32_e32 v33, 0xffff0000, v33
	v_pk_mul_f32 v[30:31], v[30:31], v[34:35]
	v_pk_mul_f32 v[28:29], v[28:29], v[32:33]
	v_cvt_pk_bf16_f32 v30, v30, v31
	v_cvt_pk_bf16_f32 v31, v28, v29
	global_store_dwordx2 v[18:19], v[30:31], off offset:32
	v_mov_b32_e32 v28, v166
	v_mov_b32_e32 v29, v167
	v_lshlrev_b32_e32 v30, 16, v28
	v_and_b32_e32 v31, 0xffff0000, v28
	v_lshlrev_b32_e32 v28, 16, v29
	v_and_b32_e32 v29, 0xffff0000, v29
	v_pk_mul_f32 v[26:27], v[26:27], v[30:31]
	v_pk_mul_f32 v[24:25], v[24:25], v[28:29]
	v_cvt_pk_bf16_f32 v26, v26, v27
	v_cvt_pk_bf16_f32 v27, v24, v25
	global_store_dwordx2 v[18:19], v[26:27], off offset:48
	v_mov_b32_e32 v24, v168
	v_mov_b32_e32 v25, v169
	v_lshlrev_b32_e32 v26, 16, v24
	v_and_b32_e32 v27, 0xffff0000, v24
	v_lshlrev_b32_e32 v24, 16, v25
	v_and_b32_e32 v25, 0xffff0000, v25
	v_pk_mul_f32 v[16:17], v[16:17], v[26:27]
	v_pk_mul_f32 v[14:15], v[14:15], v[24:25]
	v_cvt_pk_bf16_f32 v16, v16, v17
	v_cvt_pk_bf16_f32 v17, v14, v15
	global_store_dwordx2 v[18:19], v[16:17], off offset:64
	v_mov_b32_e32 v14, v170
	v_mov_b32_e32 v15, v171
	v_lshlrev_b32_e32 v16, 16, v14
	v_and_b32_e32 v17, 0xffff0000, v14
	v_lshlrev_b32_e32 v14, 16, v15
	v_and_b32_e32 v15, 0xffff0000, v15
	v_pk_mul_f32 v[12:13], v[12:13], v[16:17]
	v_pk_mul_f32 v[10:11], v[10:11], v[14:15]
	v_cvt_pk_bf16_f32 v12, v12, v13
	v_cvt_pk_bf16_f32 v13, v10, v11
	global_store_dwordx2 v[18:19], v[12:13], off offset:80
	v_mov_b32_e32 v10, v172
	v_mov_b32_e32 v11, v173
	v_lshlrev_b32_e32 v12, 16, v10
	v_and_b32_e32 v13, 0xffff0000, v10
	v_lshlrev_b32_e32 v10, 16, v11
	v_and_b32_e32 v11, 0xffff0000, v11
	v_pk_mul_f32 v[8:9], v[8:9], v[12:13]
	v_pk_mul_f32 v[6:7], v[6:7], v[10:11]
	v_cvt_pk_bf16_f32 v8, v8, v9
	v_cvt_pk_bf16_f32 v9, v6, v7
	global_store_dwordx2 v[18:19], v[8:9], off offset:96
	v_mov_b32_e32 v6, v174
	v_mov_b32_e32 v7, v175
	v_lshlrev_b32_e32 v8, 16, v6
	v_and_b32_e32 v9, 0xffff0000, v6
	v_lshlrev_b32_e32 v6, 16, v7
	v_and_b32_e32 v7, 0xffff0000, v7
	v_pk_mul_f32 v[4:5], v[4:5], v[8:9]
	v_pk_mul_f32 v[2:3], v[2:3], v[6:7]
	v_cvt_pk_bf16_f32 v4, v4, v5
	v_cvt_pk_bf16_f32 v5, v2, v3
	global_store_dwordx2 v[18:19], v[4:5], off offset:112

; DI unsigned pack2(float a, float b) { v2f f = {a, b}; return __builtin_bit_cast(unsigned, __builtin_convertvector(f, v2bf)); }
; DI float bflo(unsigned v) { return __uint_as_float(v << 16); }
; DI float bfhi(unsigned v) { return __uint_as_float(v & 0xffff0000u); }
; DI void stick_attn_phase(const Params& p, char* smem) {
;     ...
; #pragma unroll
;     for (int dc = 0; dc < 2; ++dc)
; #pragma unroll
;       for (int g4 = 0; g4 < 4; ++g4) {
;         const int d = hd * 64 + 32 * dc + 8 * g4 + 4 * h;
;         const u32x2 zz = *(const u32x2*)(p.qkvz + tok * LD + 3072 + d);
;         u32x2 o;
;         o.x = pack2(ot[dc][4 * g4] * bflo(zz.x), ot[dc][4 * g4 + 1] * bfhi(zz.x));
;         o.y = pack2(ot[dc][4 * g4 + 2] * bflo(zz.y), ot[dc][4 * g4 + 3] * bfhi(zz.y));
;         *(u32x2*)(p.u + tok * 1024 + d) = o;
;       }
.LBB0_2598:
	v_or_b32_e32 v0, s31, v115
	v_lshl_add_u64 v[2:3], v[100:101], 0, s[24:25]
	v_lshlrev_b32_e32 v0, 1, v0
	s_waitcnt vmcnt(0)
	v_lshl_add_u64 v[4:5], v[2:3], 0, v[0:1]
	global_load_dwordx2 v[144:145], v[4:5], off offset:16
	global_load_dwordx2 v[146:147], v[4:5], off offset:32
	global_load_dwordx2 v[148:149], v[4:5], off offset:48
	global_load_dwordx2 v[150:151], v[4:5], off offset:64
	global_load_dwordx2 v[152:153], v[4:5], off offset:80
	global_load_dwordx2 v[154:155], v[4:5], off offset:96
	global_load_dwordx2 v[156:157], v[4:5], off offset:112
	global_load_dwordx2 v[4:5], v[4:5], off
	v_lshlrev_b64 v[6:7], 11, v[96:97]
	v_lshl_add_u64 v[6:7], s[12:13], 0, v[6:7]
	v_mov_b32_e32 v9, v1
	v_lshl_add_u64 v[6:7], v[6:7], 0, v[0:1]
	v_or_b32_e32 v8, 16, v0
	v_lshl_add_u64 v[8:9], v[2:3], 0, v[8:9]
	s_mov_b64 s[0:1], 0
	s_waitcnt vmcnt(0)
	v_lshlrev_b32_e32 v10, 16, v4
	v_and_b32_e32 v11, 0xffff0000, v4
	v_lshlrev_b32_e32 v4, 16, v5
	v_and_b32_e32 v5, 0xffff0000, v5
	v_pk_mul_f32 v[10:11], v[32:33], v[10:11]
	v_pk_mul_f32 v[4:5], v[34:35], v[4:5]
	v_cvt_pk_bf16_f32 v10, v10, v11
	v_cvt_pk_bf16_f32 v11, v4, v5
	global_store_dwordx2 v[6:7], v[10:11], off
	v_mov_b32_e32 v4, v144
	v_mov_b32_e32 v5, v145
	v_mov_b32_e32 v9, v1
	v_or_b32_e32 v8, 32, v0
	v_lshl_add_u64 v[8:9], v[2:3], 0, v[8:9]
	v_lshlrev_b32_e32 v10, 16, v4
	v_and_b32_e32 v11, 0xffff0000, v4
	v_lshlrev_b32_e32 v4, 16, v5
	v_and_b32_e32 v5, 0xffff0000, v5
	v_pk_mul_f32 v[10:11], v[36:37], v[10:11]
	v_pk_mul_f32 v[4:5], v[38:39], v[4:5]
	v_cvt_pk_bf16_f32 v10, v10, v11
	v_cvt_pk_bf16_f32 v11, v4, v5
	global_store_dwordx2 v[6:7], v[10:11], off offset:16
	v_mov_b32_e32 v4, v146
	v_mov_b32_e32 v5, v147
	v_mov_b32_e32 v9, v1
	v_or_b32_e32 v8, 48, v0
	v_lshl_add_u64 v[8:9], v[2:3], 0, v[8:9]
	v_lshlrev_b32_e32 v10, 16, v4
	v_and_b32_e32 v11, 0xffff0000, v4
	v_lshlrev_b32_e32 v4, 16, v5
	v_and_b32_e32 v5, 0xffff0000, v5
	v_pk_mul_f32 v[10:11], v[40:41], v[10:11]
	v_pk_mul_f32 v[4:5], v[42:43], v[4:5]
	v_cvt_pk_bf16_f32 v10, v10, v11
	v_cvt_pk_bf16_f32 v11, v4, v5
	global_store_dwordx2 v[6:7], v[10:11], off offset:32
	v_mov_b32_e32 v4, v148
	v_mov_b32_e32 v5, v149
	v_mov_b32_e32 v9, v1
	v_or_b32_e32 v8, 64, v0
	v_lshl_add_u64 v[8:9], v[2:3], 0, v[8:9]
	v_lshlrev_b32_e32 v10, 16, v4
	v_and_b32_e32 v11, 0xffff0000, v4
	v_lshlrev_b32_e32 v4, 16, v5
	v_and_b32_e32 v5, 0xffff0000, v5
	v_pk_mul_f32 v[10:11], v[44:45], v[10:11]
	v_pk_mul_f32 v[4:5], v[46:47], v[4:5]
	v_cvt_pk_bf16_f32 v10, v10, v11
	v_cvt_pk_bf16_f32 v11, v4, v5
	global_store_dwordx2 v[6:7], v[10:11], off offset:48
	v_mov_b32_e32 v4, v150
	v_mov_b32_e32 v5, v151
	v_mov_b32_e32 v9, v1
	v_or_b32_e32 v8, 0x50, v0
	v_lshl_add_u64 v[8:9], v[2:3], 0, v[8:9]
	v_lshlrev_b32_e32 v10, 16, v4
	v_and_b32_e32 v11, 0xffff0000, v4
	v_lshlrev_b32_e32 v4, 16, v5
	v_and_b32_e32 v5, 0xffff0000, v5
	v_pk_mul_f32 v[10:11], v[16:17], v[10:11]
	v_pk_mul_f32 v[4:5], v[18:19], v[4:5]
	v_cvt_pk_bf16_f32 v10, v10, v11
	v_cvt_pk_bf16_f32 v11, v4, v5
	global_store_dwordx2 v[6:7], v[10:11], off offset:64
	v_mov_b32_e32 v4, v152
	v_mov_b32_e32 v5, v153
	v_mov_b32_e32 v9, v1
	v_or_b32_e32 v8, 0x60, v0
	v_lshl_add_u64 v[8:9], v[2:3], 0, v[8:9]
	v_or_b32_e32 v0, 0x70, v0
	v_lshl_add_u64 v[2:3], v[2:3], 0, v[0:1]
	v_lshlrev_b32_e32 v10, 16, v4
	v_and_b32_e32 v11, 0xffff0000, v4
	v_lshlrev_b32_e32 v4, 16, v5
	v_and_b32_e32 v5, 0xffff0000, v5
	v_pk_mul_f32 v[10:11], v[20:21], v[10:11]
	v_pk_mul_f32 v[4:5], v[22:23], v[4:5]
	v_cvt_pk_bf16_f32 v10, v10, v11
	v_cvt_pk_bf16_f32 v11, v4, v5
	global_store_dwordx2 v[6:7], v[10:11], off offset:80
	v_mov_b32_e32 v4, v154
	v_mov_b32_e32 v5, v155
	v_lshlrev_b32_e32 v8, 16, v4
	v_and_b32_e32 v9, 0xffff0000, v4
	v_lshlrev_b32_e32 v4, 16, v5
	v_and_b32_e32 v5, 0xffff0000, v5
	v_pk_mul_f32 v[8:9], v[24:25], v[8:9]
	v_pk_mul_f32 v[4:5], v[26:27], v[4:5]
	v_cvt_pk_bf16_f32 v8, v8, v9
	v_cvt_pk_bf16_f32 v9, v4, v5
	global_store_dwordx2 v[6:7], v[8:9], off offset:96
	v_mov_b32_e32 v2, v156
	v_mov_b32_e32 v3, v157
	v_lshlrev_b32_e32 v4, 16, v2
	v_and_b32_e32 v5, 0xffff0000, v2
	v_lshlrev_b32_e32 v2, 16, v3
	v_and_b32_e32 v3, 0xffff0000, v3
	v_pk_mul_f32 v[4:5], v[28:29], v[4:5]
	v_pk_mul_f32 v[2:3], v[30:31], v[2:3]
	v_cvt_pk_bf16_f32 v4, v4, v5
	v_cvt_pk_bf16_f32 v5, v2, v3
	global_store_dwordx2 v[6:7], v[4:5], off offset:112
